# w_in epilogue: f32 context-cache stores (final outputs, never re-read in the kernel) get the nt hint
# baseline (speedup 1.0000x reference)
.LBB0_521:
	v_add_u32_e32 v134, v128, v150
	v_ashrrev_i32_e32 v135, 31, v134
	v_lshl_add_u64 v[134:135], v[134:135], 2, v[154:155]
	global_store_dwordx4 v[134:135], v[124:127], off nt
	global_store_dwordx4 v[134:135], v[120:123], off offset:16 nt

.LBB0_531:
	v_ashrrev_i32_e32 v123, 31, v122
	v_lshl_add_u64 v[122:123], v[122:123], 0, v[150:151]
	v_lshl_add_u64 v[120:121], v[122:123], 2, v[120:121]
	global_store_dwordx4 v[120:121], v[116:119], off offset:512 nt
	global_store_dwordx4 v[120:121], v[112:115], off offset:528 nt

.LBB0_541:
	v_add_u32_e32 v118, v118, v150
	v_ashrrev_i32_e32 v119, 31, v118
	v_lshl_add_u64 v[114:115], v[118:119], 2, v[114:115]
	global_store_dwordx4 v[114:115], v[108:111], off nt
	global_store_dwordx4 v[114:115], v[104:107], off offset:16 nt

.LBB0_551:
	v_ashrrev_i32_e32 v107, 31, v106
	v_lshl_add_u64 v[106:107], v[106:107], 0, v[150:151]
	v_lshl_add_u64 v[104:105], v[106:107], 2, v[104:105]
	global_store_dwordx4 v[104:105], v[100:103], off offset:512 nt
	global_store_dwordx4 v[104:105], v[96:99], off offset:528 nt

.LBB0_561:
	v_add_u32_e32 v102, v102, v150
	v_ashrrev_i32_e32 v103, 31, v102
	v_lshl_add_u64 v[98:99], v[102:103], 2, v[98:99]
	global_store_dwordx4 v[98:99], v[92:95], off nt
	global_store_dwordx4 v[98:99], v[88:91], off offset:16 nt

.LBB0_571:
	v_ashrrev_i32_e32 v91, 31, v90
	v_lshl_add_u64 v[90:91], v[90:91], 0, v[150:151]
	v_lshl_add_u64 v[88:89], v[90:91], 2, v[88:89]
	global_store_dwordx4 v[88:89], v[84:87], off offset:512 nt
	global_store_dwordx4 v[88:89], v[80:83], off offset:528 nt

.LBB0_581:
	v_add_u32_e32 v86, v86, v150
	v_ashrrev_i32_e32 v87, 31, v86
	v_lshl_add_u64 v[82:83], v[86:87], 2, v[82:83]
	global_store_dwordx4 v[82:83], v[76:79], off nt
	global_store_dwordx4 v[82:83], v[72:75], off offset:16 nt

.LBB0_591:
	v_ashrrev_i32_e32 v75, 31, v74
	v_lshl_add_u64 v[74:75], v[74:75], 0, v[150:151]
	v_lshl_add_u64 v[72:73], v[74:75], 2, v[72:73]
	global_store_dwordx4 v[72:73], v[68:71], off offset:512 nt
	global_store_dwordx4 v[72:73], v[64:67], off offset:528 nt

.LBB0_601:
	v_add_u32_e32 v70, v70, v150
	v_ashrrev_i32_e32 v71, 31, v70
	v_lshl_add_u64 v[66:67], v[70:71], 2, v[66:67]
	global_store_dwordx4 v[66:67], v[60:63], off nt
	global_store_dwordx4 v[66:67], v[56:59], off offset:16 nt

.LBB0_611:
	v_ashrrev_i32_e32 v59, 31, v58
	v_lshl_add_u64 v[58:59], v[58:59], 0, v[150:151]
	v_lshl_add_u64 v[56:57], v[58:59], 2, v[56:57]
	global_store_dwordx4 v[56:57], v[52:55], off offset:512 nt
	global_store_dwordx4 v[56:57], v[48:51], off offset:528 nt

.LBB0_621:
	v_add_u32_e32 v54, v54, v150
	v_ashrrev_i32_e32 v55, 31, v54
	v_lshl_add_u64 v[50:51], v[54:55], 2, v[50:51]
	global_store_dwordx4 v[50:51], v[44:47], off nt
	global_store_dwordx4 v[50:51], v[40:43], off offset:16 nt

.LBB0_631:
	v_ashrrev_i32_e32 v43, 31, v42
	v_lshl_add_u64 v[42:43], v[42:43], 0, v[150:151]
	v_lshl_add_u64 v[40:41], v[42:43], 2, v[40:41]
	global_store_dwordx4 v[40:41], v[36:39], off offset:512 nt
	global_store_dwordx4 v[40:41], v[32:35], off offset:528 nt

.LBB0_641:
	v_add_u32_e32 v38, v38, v150
	v_ashrrev_i32_e32 v39, 31, v38
	v_lshl_add_u64 v[34:35], v[38:39], 2, v[34:35]
	global_store_dwordx4 v[34:35], v[28:31], off nt
	global_store_dwordx4 v[34:35], v[24:27], off offset:16 nt

.LBB0_651:
	v_ashrrev_i32_e32 v27, 31, v26
	v_lshl_add_u64 v[26:27], v[26:27], 0, v[150:151]
	v_lshl_add_u64 v[24:25], v[26:27], 2, v[24:25]
	global_store_dwordx4 v[24:25], v[20:23], off offset:512 nt
	global_store_dwordx4 v[24:25], v[16:19], off offset:528 nt

.LBB0_661:
	v_add_u32_e32 v22, v22, v150
	v_ashrrev_i32_e32 v23, 31, v22
	v_lshl_add_u64 v[18:19], v[22:23], 2, v[18:19]
	global_store_dwordx4 v[18:19], v[12:15], off nt
	global_store_dwordx4 v[18:19], v[8:11], off offset:16 nt

.LBB0_671:
	v_ashrrev_i32_e32 v11, 31, v10
	v_lshl_add_u64 v[10:11], v[10:11], 0, v[150:151]
	v_lshl_add_u64 v[8:9], v[10:11], 2, v[8:9]
	global_store_dwordx4 v[8:9], v[4:7], off offset:512 nt
	global_store_dwordx4 v[8:9], v[0:3], off offset:528 nt
